# deferred-max loop QK: sub-block-major K order, prefetch address VALU and row-max chain interleaved into MFMA gaps
# baseline (speedup 1.0000x reference)
; #define LAS __attribute__((address_space(3)))
; template <bool DOK, bool DOV>
; __device__ __forceinline__ void stage_load(StageRegs& R, const bf16_t* Kg, const bf16_t* VTg, int vpitch, int key0, int tid) {
; #pragma unroll
;     for (int i = 0; i < 2; ++i) {
;         const int idx = tid + i * 512;
;         if (DOK) R.k[i] = *(const u32x4*)(Kg + (size_t)(key0 + (idx >> 4)) * 128 + (idx & 15) * 8);
;         if (DOV) R.v[i] = *(const u32x4*)(VTg + (size_t)(idx >> 3) * vpitch + key0 + (idx & 7) * 8);
;     }
; #pragma unroll
;     for (int sub = 0; sub < 4; ++sub) { s[0][sub] = (f32x4){init0, init0, init0, init0}; s[1][sub] = (f32x4){init1, init1, init1, init1}; }
; #pragma unroll
;     for (int kc = 0; kc < 4; ++kc) {
;         bf16x8 kf[4];
; #pragma unroll
;         for (int sub = 0; sub < 4; ++sub) kf[sub] = *(const LAS bf16x8*)(buf + (16 * sub + ql) * KT_PITCH + kc * 64 + g * 16);
; #pragma unroll
;         for (int sub = 0; sub < 4; ++sub) {
;             s[0][sub] = __builtin_amdgcn_mfma_f32_16x16x32_bf16(kf[sub], qf[0][kc], s[0][sub], 0, 0, 0);
;             s[1][sub] = __builtin_amdgcn_mfma_f32_16x16x32_bf16(kf[sub], qf[1][kc], s[1][sub], 0, 0, 0);
;         }
;         if (kc & 1) asm volatile("" ::: "memory");
;     }
; }
; template <int MODE, bool DEFER> ...
;     ...
;     if (DEFER) qk_tile2(s, qf, buf, ql, g, take[0] ? -mrun[0] : -__builtin_inff(), take[1] ? -mrun[1] : -__builtin_inff());
;     else qk_tile2(s, qf, buf, ql, g);
;     if (tile < tile_hi) stage_load<true, true>(R, Kg, VTg, vpitch, (tile + 1) * 64, tid);
;     u32x4 pk[2][2];
;     if (DEFER) {
;         float m0 = local_max16(s[0]), m1 = local_max16(s[1]);
;         if (__any(m0 > DEFER_THRESH || m1 > DEFER_THRESH)) {
.LBB0_1008:
	s_bitcmp1_b32 s1, 0
	s_cselect_b32 s7, 0x8c00, 0
	s_add_i32 s11, s7, 0
	s_lshl_b64 s[12:13], 1, s1
	s_ashr_i32 s7, s6, 31
	v_add3_u32 v157, s11, v149, v201
	ds_read_b128 v[180:183], v157
	ds_read_b128 v[184:187], v157 offset:64
	ds_read_b128 v[188:191], v157 offset:128
	ds_read_b128 v[196:199], v157 offset:192
	ds_read_b128 v[212:215], v157 offset:4352
	v_and_b32_e32 v245, s13, v175
	v_and_b32_e32 v244, s12, v174
	v_and_b32_e32 v247, s13, v173
	v_and_b32_e32 v246, s12, v172
	v_cmp_ne_u64_e32 vcc, 0, v[244:245]
	s_nop 0
	s_nop 0
	v_cndmask_b32_e64 v244, v235, -v170, vcc
	v_cmp_ne_u64_e32 vcc, 0, v[246:247]
	v_mov_b32_e32 v245, v244
	v_mov_b32_e32 v246, v244
	v_cndmask_b32_e64 v248, v235, -v171, vcc
	v_mov_b32_e32 v247, v244
	v_mov_b32_e32 v249, v248
	v_mov_b32_e32 v250, v248
	v_mov_b32_e32 v251, v248
	s_waitcnt lgkmcnt(4)
	v_mfma_f32_16x16x32_bf16 v[144:147], v[180:183], v[4:7], v[244:247]
	v_mfma_f32_16x16x32_bf16 v[128:131], v[180:183], v[20:23], v[248:251]
	ds_read_b128 v[180:183], v157 offset:4416
	v_add_u32_e32 v44, s6, v152
	v_ashrrev_i32_e32 v45, 31, v44
	s_waitcnt lgkmcnt(4)
	v_mfma_f32_16x16x32_bf16 v[144:147], v[184:187], v[8:11], v[144:147]
	v_mfma_f32_16x16x32_bf16 v[128:131], v[184:187], v[24:27], v[128:131]
	ds_read_b128 v[184:187], v157 offset:4480
	v_lshlrev_b64 v[44:45], 8, v[44:45]
	v_lshl_add_u64 v[44:45], v[176:177], 0, v[44:45]
	s_waitcnt lgkmcnt(4)
	v_mfma_f32_16x16x32_bf16 v[144:147], v[188:191], v[12:15], v[144:147]
	v_mfma_f32_16x16x32_bf16 v[128:131], v[188:191], v[28:31], v[128:131]
	ds_read_b128 v[188:191], v157 offset:4544
	global_load_dwordx4 v[44:47], v[44:45], off
	v_lshl_add_u64 v[48:49], s[6:7], 1, v[178:179]
	s_waitcnt lgkmcnt(4)
	v_mfma_f32_16x16x32_bf16 v[144:147], v[196:199], v[16:19], v[144:147]
	v_mfma_f32_16x16x32_bf16 v[128:131], v[196:199], v[32:35], v[128:131]
	ds_read_b128 v[196:199], v157 offset:8704
	v_add_u32_e32 v36, s6, v150
	v_ashrrev_i32_e32 v37, 31, v36
	s_waitcnt lgkmcnt(4)
	v_mfma_f32_16x16x32_bf16 v[140:143], v[212:215], v[4:7], v[244:247]
	v_mfma_f32_16x16x32_bf16 v[124:127], v[212:215], v[20:23], v[248:251]
	ds_read_b128 v[212:215], v157 offset:8768
	v_lshlrev_b64 v[36:37], 8, v[36:37]
	v_lshl_add_u64 v[36:37], v[176:177], 0, v[36:37]
	s_waitcnt lgkmcnt(4)
	v_mfma_f32_16x16x32_bf16 v[140:143], v[180:183], v[8:11], v[140:143]
	v_mfma_f32_16x16x32_bf16 v[124:127], v[180:183], v[24:27], v[124:127]
	ds_read_b128 v[180:183], v157 offset:8832
	global_load_dwordx4 v[36:39], v[36:37], off
	v_lshl_add_u64 v[40:41], v[48:49], 0, v[164:165]
	s_waitcnt lgkmcnt(4)
	v_mfma_f32_16x16x32_bf16 v[140:143], v[184:187], v[12:15], v[140:143]
	v_mfma_f32_16x16x32_bf16 v[124:127], v[184:187], v[28:31], v[124:127]
	ds_read_b128 v[184:187], v157 offset:8896
	v_lshl_add_u64 v[48:49], v[48:49], 0, v[166:167]
	global_load_dwordx4 v[40:43], v[40:41], off
	s_waitcnt lgkmcnt(4)
	v_mfma_f32_16x16x32_bf16 v[140:143], v[188:191], v[16:19], v[140:143]
	v_mfma_f32_16x16x32_bf16 v[124:127], v[188:191], v[32:35], v[124:127]
	ds_read_b128 v[188:191], v157 offset:13056
	global_load_dwordx4 v[48:51], v[48:49], off
	v_max3_f32 v3, v144, v144, v145
	s_waitcnt lgkmcnt(4)
	v_mfma_f32_16x16x32_bf16 v[136:139], v[196:199], v[4:7], v[244:247]
	v_mfma_f32_16x16x32_bf16 v[120:123], v[196:199], v[20:23], v[248:251]
	ds_read_b128 v[196:199], v157 offset:13120
	v_max3_f32 v3, v3, v146, v147
	v_max3_f32 v151, v128, v128, v129
	s_waitcnt lgkmcnt(4)
	v_mfma_f32_16x16x32_bf16 v[136:139], v[212:215], v[8:11], v[136:139]
	v_mfma_f32_16x16x32_bf16 v[120:123], v[212:215], v[24:27], v[120:123]
	ds_read_b128 v[212:215], v157 offset:13184
	v_max3_f32 v151, v151, v130, v131
	v_max3_f32 v3, v3, v140, v141
	s_waitcnt lgkmcnt(4)
	v_mfma_f32_16x16x32_bf16 v[136:139], v[180:183], v[12:15], v[136:139]
	v_mfma_f32_16x16x32_bf16 v[120:123], v[180:183], v[28:31], v[120:123]
	ds_read_b128 v[180:183], v157 offset:13248
	v_max3_f32 v3, v3, v142, v143
	v_max3_f32 v151, v151, v124, v125
	s_waitcnt lgkmcnt(4)
	v_mfma_f32_16x16x32_bf16 v[136:139], v[184:187], v[16:19], v[136:139]
	v_mfma_f32_16x16x32_bf16 v[120:123], v[184:187], v[32:35], v[120:123]
	v_max3_f32 v151, v151, v126, v127
	s_waitcnt lgkmcnt(3)
	v_mfma_f32_16x16x32_bf16 v[132:135], v[188:191], v[4:7], v[244:247]
	v_mfma_f32_16x16x32_bf16 v[116:119], v[188:191], v[20:23], v[248:251]
	s_waitcnt lgkmcnt(2)
	v_mfma_f32_16x16x32_bf16 v[132:135], v[196:199], v[8:11], v[132:135]
	v_mfma_f32_16x16x32_bf16 v[116:119], v[196:199], v[24:27], v[116:119]
	s_waitcnt lgkmcnt(1)
	v_mfma_f32_16x16x32_bf16 v[132:135], v[212:215], v[12:15], v[132:135]
	v_mfma_f32_16x16x32_bf16 v[116:119], v[212:215], v[28:31], v[116:119]
	v_max3_f32 v3, v3, v136, v137
	v_max3_f32 v3, v3, v138, v139
	s_waitcnt lgkmcnt(0)
	v_mfma_f32_16x16x32_bf16 v[132:135], v[180:183], v[16:19], v[132:135]
	v_mfma_f32_16x16x32_bf16 v[116:119], v[180:183], v[32:35], v[116:119]
	v_max3_f32 v151, v151, v120, v121
	v_max3_f32 v151, v151, v122, v123
	s_nop 6
	v_max3_f32 v3, v3, v132, v133
	v_max3_f32 v3, v3, v134, v135
	v_max3_f32 v151, v151, v116, v117
	v_max3_f32 v151, v151, v118, v119
	v_max_f32_e32 v157, v3, v3
	v_max_f32_e32 v153, v151, v151
	v_max_f32_e32 v153, v157, v153
	v_cmp_lt_f32_e32 vcc, s94, v153
	s_cbranch_vccz .LBB0_1007
; template <int MODE, bool DEFER> ...
;     ...
;             m0 = fmaxf(qmax(m0), 0.f); m1 = fmaxf(qmax(m1), 0.f);
;             const float a0 = __builtin_amdgcn_exp2f(-m0), a1 = __builtin_amdgcn_exp2f(-m1);
;             mrun[0] += m0; mrun[1] += m1; lsum[0] *= a0; lsum[1] *= a1;
; #pragma unroll
;             for (int dt = 0; dt < 8; ++dt) { o[0][dt] = o[0][dt] * a0; o[1][dt] = o[1][dt] * a1; }
; #pragma unroll
;             for (int sub = 0; sub < 4; ++sub) { s[0][sub] = s[0][sub] - m0; s[1][sub] = s[1][sub] - m1; }
	v_mov_b32_e32 v153, v3
	s_nop 1
	v_permlane32_swap_b32_e32 v3, v153
	v_max_f32_e32 v153, v153, v153
	v_max_f32_e32 v3, v3, v3
	v_max_f32_e32 v3, v3, v153
	v_mov_b32_e32 v153, v3
	s_nop 1
	v_permlane16_swap_b32_e32 v3, v153
	v_max3_f32 v180, v3, v153, 0
	v_mov_b32_e32 v3, v151
	s_nop 1
	v_permlane32_swap_b32_e32 v151, v3
	v_max_f32_e32 v3, v3, v3
	v_max_f32_e32 v151, v151, v151
	v_max_f32_e32 v3, v151, v3
	v_mov_b32_e32 v151, v3
	s_nop 1
	v_permlane16_swap_b32_e32 v3, v151
	v_max3_f32 v181, v3, v151, 0
	v_exp_f32_e64 v183, -v180
	v_exp_f32_e64 v182, -v181
	v_pk_add_f32 v[170:171], v[170:171], v[180:181]
	v_sub_f32_e32 v144, v144, v180
	v_mov_b32_e32 v184, v183
	v_pk_mul_f32 v[168:169], v[168:169], v[182:183]
	v_pk_mul_f32 v[106:107], v[106:107], v[184:185] op_sel_hi:[1,0]
	v_pk_mul_f32 v[104:105], v[104:105], v[184:185] op_sel_hi:[1,0]
	v_pk_mul_f32 v[82:83], v[82:83], v[182:183] op_sel_hi:[1,0]
	v_pk_mul_f32 v[80:81], v[80:81], v[182:183] op_sel_hi:[1,0]
	v_pk_mul_f32 v[110:111], v[110:111], v[184:185] op_sel_hi:[1,0]
	v_pk_mul_f32 v[108:109], v[108:109], v[184:185] op_sel_hi:[1,0]
	v_pk_mul_f32 v[78:79], v[78:79], v[182:183] op_sel_hi:[1,0]
	v_pk_mul_f32 v[76:77], v[76:77], v[182:183] op_sel_hi:[1,0]
	v_pk_mul_f32 v[102:103], v[102:103], v[184:185] op_sel_hi:[1,0]
	v_pk_mul_f32 v[100:101], v[100:101], v[184:185] op_sel_hi:[1,0]
	v_pk_mul_f32 v[74:75], v[74:75], v[182:183] op_sel_hi:[1,0]
	v_pk_mul_f32 v[72:73], v[72:73], v[182:183] op_sel_hi:[1,0]
	v_pk_mul_f32 v[98:99], v[98:99], v[184:185] op_sel_hi:[1,0]
	v_pk_mul_f32 v[96:97], v[96:97], v[184:185] op_sel_hi:[1,0]
	v_pk_mul_f32 v[70:71], v[70:71], v[182:183] op_sel_hi:[1,0]
	v_pk_mul_f32 v[68:69], v[68:69], v[182:183] op_sel_hi:[1,0]
	v_pk_mul_f32 v[90:91], v[90:91], v[184:185] op_sel_hi:[1,0]
	v_pk_mul_f32 v[88:89], v[88:89], v[184:185] op_sel_hi:[1,0]
	v_pk_mul_f32 v[62:63], v[62:63], v[182:183] op_sel_hi:[1,0]
	v_pk_mul_f32 v[60:61], v[60:61], v[182:183] op_sel_hi:[1,0]
	v_pk_mul_f32 v[86:87], v[86:87], v[184:185] op_sel_hi:[1,0]
	v_pk_mul_f32 v[84:85], v[84:85], v[184:185] op_sel_hi:[1,0]
	v_pk_mul_f32 v[54:55], v[54:55], v[182:183] op_sel_hi:[1,0]
	v_pk_mul_f32 v[52:53], v[52:53], v[182:183] op_sel_hi:[1,0]
	v_pk_mul_f32 v[94:95], v[94:95], v[184:185] op_sel_hi:[1,0]
	v_pk_mul_f32 v[92:93], v[92:93], v[184:185] op_sel_hi:[1,0]
	v_pk_mul_f32 v[66:67], v[66:67], v[182:183] op_sel_hi:[1,0]
	v_pk_mul_f32 v[64:65], v[64:65], v[182:183] op_sel_hi:[1,0]
	v_pk_mul_f32 v[114:115], v[114:115], v[184:185] op_sel_hi:[1,0]
	v_pk_mul_f32 v[112:113], v[112:113], v[184:185] op_sel_hi:[1,0]
	v_pk_mul_f32 v[58:59], v[58:59], v[182:183] op_sel_hi:[1,0]
	v_pk_mul_f32 v[56:57], v[56:57], v[182:183] op_sel_hi:[1,0]
	v_sub_f32_e32 v145, v145, v180
	v_sub_f32_e32 v146, v146, v180
	v_sub_f32_e32 v147, v147, v180
	v_sub_f32_e32 v128, v128, v181
	v_sub_f32_e32 v129, v129, v181
	v_sub_f32_e32 v130, v130, v181
	v_sub_f32_e32 v131, v131, v181
	v_sub_f32_e32 v140, v140, v180
	v_sub_f32_e32 v141, v141, v180
	v_sub_f32_e32 v142, v142, v180
	v_sub_f32_e32 v143, v143, v180
	v_sub_f32_e32 v124, v124, v181
	v_sub_f32_e32 v125, v125, v181
	v_sub_f32_e32 v126, v126, v181
	v_sub_f32_e32 v127, v127, v181
	v_sub_f32_e32 v136, v136, v180
	v_sub_f32_e32 v137, v137, v180
	v_sub_f32_e32 v138, v138, v180
	v_sub_f32_e32 v139, v139, v180
	v_sub_f32_e32 v120, v120, v181
	v_sub_f32_e32 v121, v121, v181
	v_sub_f32_e32 v122, v122, v181
	v_sub_f32_e32 v123, v123, v181
	v_sub_f32_e32 v132, v132, v180
	v_sub_f32_e32 v133, v133, v180
	v_sub_f32_e32 v134, v134, v180
	v_sub_f32_e32 v135, v135, v180
	v_sub_f32_e32 v116, v116, v181
	v_sub_f32_e32 v117, v117, v181
	v_sub_f32_e32 v118, v118, v181
	v_sub_f32_e32 v119, v119, v181
	s_branch .LBB0_1007
